# v088 + counted lgkmcnt waits in the two PV sections of the attention unit epilogue
# speedup vs baseline: 1.0007x; 1.0007x over previous
.LBB0_589:
	v_exp_f32_e32 v130, v98
	v_add_f32_e32 v98, 0, v127
	v_add_f32_e32 v98, v129, v98
	v_add_f32_e32 v98, v125, v98
	v_add_f32_e32 v98, v128, v98
	v_add_f32_e32 v98, v123, v98
	v_add_f32_e32 v98, v126, v98
	v_add_f32_e32 v98, v122, v98
	v_add_f32_e32 v98, v124, v98
	v_add_f32_e32 v98, v119, v98
	v_add_f32_e32 v98, v121, v98
	v_add_f32_e32 v98, v117, v98
	v_add_f32_e32 v98, v120, v98
	v_add_f32_e32 v98, v115, v98
	v_exp_f32_e32 v132, v99
	v_add_f32_e32 v98, v118, v98
	v_exp_f32_e32 v133, v100
	v_add_f32_e32 v98, v114, v98
	v_exp_f32_e32 v134, v101
	v_add_f32_e32 v98, v116, v98
	v_exp_f32_e32 v135, v102
	v_add_f32_e32 v98, v130, v98
	v_exp_f32_e32 v136, v103
	v_add_f32_e32 v98, v132, v98
	v_exp_f32_e32 v137, v104
	v_add_f32_e32 v98, v133, v98
	v_exp_f32_e32 v138, v105
	v_add_f32_e32 v98, v134, v98
	v_exp_f32_e32 v139, v106
	v_add_f32_e32 v98, v135, v98
	v_exp_f32_e32 v140, v107
	v_add_f32_e32 v98, v136, v98
	v_exp_f32_e32 v141, v108
	v_add_f32_e32 v98, v137, v98
	v_exp_f32_e32 v142, v109
	v_add_f32_e32 v98, v138, v98
	v_exp_f32_e32 v143, v110
	v_add_f32_e32 v98, v139, v98
	v_exp_f32_e32 v144, v111
	v_add_f32_e32 v98, v140, v98
	v_exp_f32_e32 v145, v112
	v_add_f32_e32 v98, v141, v98
	v_exp_f32_e32 v146, v113
	v_add_f32_e32 v98, v142, v98
	v_add_f32_e32 v98, v143, v98
	v_add_f32_e32 v98, v144, v98
	v_add_f32_e32 v98, v145, v98
	v_add_f32_e32 v98, v146, v98
	v_mov_b32_e32 v99, v98
	v_cvt_pk_bf16_f32 v100, v127, v129
	v_cvt_pk_bf16_f32 v101, v125, v128
	v_cvt_pk_bf16_f32 v102, v123, v126
	v_cvt_pk_bf16_f32 v103, v122, v124
	s_nop 1
	v_permlane32_swap_b32_e32 v98, v99
	v_permlane32_swap_b32_e32 v100, v102
	v_permlane32_swap_b32_e32 v101, v103
	v_cvt_pk_bf16_f32 v104, v119, v121
	v_cvt_pk_bf16_f32 v105, v117, v120
	v_cvt_pk_bf16_f32 v106, v115, v118
	v_cvt_pk_bf16_f32 v107, v114, v116
	v_cvt_pk_bf16_f32 v108, v130, v132
	v_cvt_pk_bf16_f32 v109, v133, v134
	v_cvt_pk_bf16_f32 v110, v135, v136
	v_cvt_pk_bf16_f32 v111, v137, v138
	v_cvt_pk_bf16_f32 v112, v139, v140
	v_cvt_pk_bf16_f32 v113, v141, v142
	v_cvt_pk_bf16_f32 v114, v143, v144
	v_cvt_pk_bf16_f32 v115, v145, v146
	s_nop 0
	v_permlane32_swap_b32_e32 v104, v106
	v_permlane32_swap_b32_e32 v105, v107
	v_permlane32_swap_b32_e32 v108, v110
	v_permlane32_swap_b32_e32 v109, v111
	v_permlane32_swap_b32_e32 v112, v114
	v_permlane32_swap_b32_e32 v113, v115
	ds_read_b64_tr_b16 v[116:117], v176 offset:0
	ds_read_b64_tr_b16 v[118:119], v176 offset:0x800
	ds_read_b64_tr_b16 v[120:121], v176 offset:0x1000
	ds_read_b64_tr_b16 v[122:123], v176 offset:0x1800
	ds_read_b64_tr_b16 v[124:125], v176 offset:0x2000
	ds_read_b64_tr_b16 v[126:127], v176 offset:0x2800
	ds_read_b64_tr_b16 v[132:133], v176 offset:0x3000
	ds_read_b64_tr_b16 v[134:135], v176 offset:0x3800
	s_nop 0
	s_waitcnt lgkmcnt(6)
	v_mfma_f32_32x32x16_bf16 v[50:65], v[100:103], v[116:119], v[50:65]
	ds_read_b64_tr_b16 v[116:117], v176 offset:0x200
	ds_read_b64_tr_b16 v[118:119], v176 offset:0xa00
	s_waitcnt lgkmcnt(6)
	v_mfma_f32_32x32x16_bf16 v[50:65], v[104:107], v[120:123], v[50:65]
	ds_read_b64_tr_b16 v[120:121], v176 offset:0x1200
	ds_read_b64_tr_b16 v[122:123], v176 offset:0x1a00
	s_waitcnt lgkmcnt(6)
	v_mfma_f32_32x32x16_bf16 v[50:65], v[108:111], v[124:127], v[50:65]
	ds_read_b64_tr_b16 v[124:125], v176 offset:0x2200
	ds_read_b64_tr_b16 v[126:127], v176 offset:0x2a00
	s_waitcnt lgkmcnt(6)
	v_mfma_f32_32x32x16_bf16 v[50:65], v[112:115], v[132:135], v[50:65]
	ds_read_b64_tr_b16 v[132:133], v176 offset:0x3200
	ds_read_b64_tr_b16 v[134:135], v176 offset:0x3a00
	s_waitcnt lgkmcnt(6)
	v_mfma_f32_32x32x16_bf16 v[34:49], v[100:103], v[116:119], v[34:49]
	ds_read_b64_tr_b16 v[116:117], v176 offset:0x400
	ds_read_b64_tr_b16 v[118:119], v176 offset:0xc00
	s_waitcnt lgkmcnt(6)
	v_mfma_f32_32x32x16_bf16 v[34:49], v[104:107], v[120:123], v[34:49]
	ds_read_b64_tr_b16 v[120:121], v176 offset:0x1400
	ds_read_b64_tr_b16 v[122:123], v176 offset:0x1c00
	s_waitcnt lgkmcnt(6)
	v_mfma_f32_32x32x16_bf16 v[34:49], v[108:111], v[124:127], v[34:49]
	ds_read_b64_tr_b16 v[124:125], v176 offset:0x2400
	ds_read_b64_tr_b16 v[126:127], v176 offset:0x2c00
	s_waitcnt lgkmcnt(6)
	v_mfma_f32_32x32x16_bf16 v[34:49], v[112:115], v[132:135], v[34:49]
	ds_read_b64_tr_b16 v[132:133], v176 offset:0x3400
	ds_read_b64_tr_b16 v[134:135], v176 offset:0x3c00
	s_waitcnt lgkmcnt(6)
	v_mfma_f32_32x32x16_bf16 v[18:33], v[100:103], v[116:119], v[18:33]
	ds_read_b64_tr_b16 v[116:117], v176 offset:0x600
	ds_read_b64_tr_b16 v[118:119], v176 offset:0xe00
	s_waitcnt lgkmcnt(6)
	v_mfma_f32_32x32x16_bf16 v[18:33], v[104:107], v[120:123], v[18:33]
	ds_read_b64_tr_b16 v[120:121], v176 offset:0x1600
	ds_read_b64_tr_b16 v[122:123], v176 offset:0x1e00
	s_waitcnt lgkmcnt(6)
	v_mfma_f32_32x32x16_bf16 v[18:33], v[108:111], v[124:127], v[18:33]
	ds_read_b64_tr_b16 v[124:125], v176 offset:0x2600
	ds_read_b64_tr_b16 v[126:127], v176 offset:0x2e00
	s_waitcnt lgkmcnt(6)
	v_mfma_f32_32x32x16_bf16 v[18:33], v[112:115], v[132:135], v[18:33]
	ds_read_b64_tr_b16 v[132:133], v176 offset:0x3600
	ds_read_b64_tr_b16 v[134:135], v176 offset:0x3e00
	s_waitcnt lgkmcnt(6)
	v_mfma_f32_32x32x16_bf16 v[2:17], v[100:103], v[116:119], v[2:17]
	v_max_f32_e32 v100, v83, v83
	v_max_f32_e32 v101, v82, v82
	v_max_f32_e32 v100, v101, v100
	v_max3_f32 v100, v100, v84, v85
	v_max3_f32 v100, v100, v86, v87
	v_max3_f32 v100, v100, v88, v89
	v_max3_f32 v100, v100, v90, v91
	v_max3_f32 v100, v100, v92, v93
	v_max3_f32 v100, v100, v94, v95
	s_waitcnt lgkmcnt(4)
	v_mfma_f32_32x32x16_bf16 v[2:17], v[104:107], v[120:123], v[2:17]
	v_max3_f32 v100, v100, v96, v97
	v_max3_f32 v100, v100, v66, v67
	v_max3_f32 v100, v100, v68, v69
	v_max3_f32 v100, v100, v70, v71
	v_max3_f32 v100, v100, v72, v73
	v_max3_f32 v100, v100, v74, v75
	v_max3_f32 v100, v100, v76, v77
	v_max3_f32 v100, v100, v78, v79
	s_waitcnt lgkmcnt(2)
	v_mfma_f32_32x32x16_bf16 v[2:17], v[108:111], v[124:127], v[2:17]
	v_max3_f32 v100, v100, v80, v81
	v_mov_b32_e32 v101, v100
	s_nop 1
	v_permlane32_swap_b32_e32 v100, v101
	v_max_f32_e32 v101, v101, v101
	v_max_f32_e32 v100, v100, v100
	v_max_f32_e32 v100, v100, v101
	v_sub_f32_e32 v101, v100, v193
	v_cmp_ge_f32_e32 vcc, s91, v101
	v_max_f32_e32 v101, v193, v193
	v_max_f32_e32 v101, v101, v100
	s_waitcnt lgkmcnt(0)
	v_mfma_f32_32x32x16_bf16 v[2:17], v[112:115], v[132:135], v[2:17]
	v_sub_f32_e32 v100, v193, v101
	v_mul_f32_e32 v100, 0x3e0293ee, v100
	v_exp_f32_e32 v100, v100
	s_cmp_eq_u64 vcc, exec
	s_cselect_b64 s[0:1], -1, 0
	s_waitcnt lgkmcnt(0)
	s_waitcnt vmcnt(0)
	s_barrier
	v_cndmask_b32_e64 v100, v100, 1.0, s[0:1]
	v_cmp_gt_f32_e32 vcc, 1.0, v100
	s_cbranch_vccz .LBB0_593
	v_cmp_gt_u32_e32 vcc, 32, v165
	s_and_saveexec_b64 s[12:13], vcc
	ds_write_b32 v177, v100 offset:128
	s_or_b64 exec, exec, s[12:13]
	s_waitcnt lgkmcnt(0)
	v_add_u32_e32 v114, s70, v164
	ds_read_b128 v[102:105], v114 offset:224
	ds_read_b128 v[106:109], v114 offset:192
	ds_read_b128 v[110:113], v114 offset:160
	ds_read_b128 v[114:117], v114 offset:128
	s_waitcnt lgkmcnt(3)
	v_pk_mul_f32 v[62:63], v[62:63], v[102:103]
	s_waitcnt lgkmcnt(2)
	v_pk_mul_f32 v[58:59], v[58:59], v[106:107]
	s_waitcnt lgkmcnt(1)
	v_pk_mul_f32 v[54:55], v[54:55], v[110:111]
	v_pk_mul_f32 v[64:65], v[64:65], v[104:105]
	v_pk_mul_f32 v[60:61], v[60:61], v[108:109]
	v_pk_mul_f32 v[56:57], v[56:57], v[112:113]
	s_waitcnt lgkmcnt(0)
	v_pk_mul_f32 v[52:53], v[52:53], v[116:117]
	v_pk_mul_f32 v[50:51], v[50:51], v[114:115]
	v_pk_mul_f32 v[46:47], v[46:47], v[102:103]
	v_pk_mul_f32 v[42:43], v[42:43], v[106:107]
	v_pk_mul_f32 v[38:39], v[38:39], v[110:111]
	v_pk_mul_f32 v[48:49], v[48:49], v[104:105]
	v_pk_mul_f32 v[44:45], v[44:45], v[108:109]
	v_pk_mul_f32 v[40:41], v[40:41], v[112:113]
	v_pk_mul_f32 v[36:37], v[36:37], v[116:117]
	v_pk_mul_f32 v[34:35], v[34:35], v[114:115]
	v_pk_mul_f32 v[30:31], v[30:31], v[102:103]
	v_pk_mul_f32 v[26:27], v[26:27], v[106:107]
	v_pk_mul_f32 v[22:23], v[22:23], v[110:111]
	v_pk_mul_f32 v[32:33], v[32:33], v[104:105]
	v_pk_mul_f32 v[28:29], v[28:29], v[108:109]
	v_pk_mul_f32 v[24:25], v[24:25], v[112:113]
	v_pk_mul_f32 v[20:21], v[20:21], v[116:117]
	v_pk_mul_f32 v[18:19], v[18:19], v[114:115]
	v_pk_mul_f32 v[14:15], v[14:15], v[102:103]
	v_pk_mul_f32 v[10:11], v[10:11], v[106:107]
	v_pk_mul_f32 v[6:7], v[6:7], v[110:111]
	v_pk_mul_f32 v[16:17], v[16:17], v[104:105]
	v_pk_mul_f32 v[12:13], v[12:13], v[108:109]
	v_pk_mul_f32 v[8:9], v[8:9], v[112:113]
	v_pk_mul_f32 v[4:5], v[4:5], v[116:117]
	v_pk_mul_f32 v[2:3], v[2:3], v[114:115]
.LBB0_593:
	v_cndmask_b32_e64 v101, v101, v193, s[0:1]
	v_mul_f32_e32 v102, 0xbe0293ee, v101
	v_fmamk_f32 v82, v82, 0x3e0293ee, v102
	v_fmamk_f32 v83, v83, 0x3e0293ee, v102
	v_fmamk_f32 v84, v84, 0x3e0293ee, v102
	v_fmamk_f32 v85, v85, 0x3e0293ee, v102
	v_fmamk_f32 v86, v86, 0x3e0293ee, v102
	v_fmamk_f32 v87, v87, 0x3e0293ee, v102
	v_fmamk_f32 v88, v88, 0x3e0293ee, v102
	v_fmamk_f32 v89, v89, 0x3e0293ee, v102
	v_fmamk_f32 v90, v90, 0x3e0293ee, v102
	v_fmamk_f32 v91, v91, 0x3e0293ee, v102
	v_fmamk_f32 v92, v92, 0x3e0293ee, v102
	v_fmamk_f32 v93, v93, 0x3e0293ee, v102
	v_fmamk_f32 v94, v94, 0x3e0293ee, v102
	v_fmamk_f32 v95, v95, 0x3e0293ee, v102
	v_fmamk_f32 v96, v96, 0x3e0293ee, v102
	v_fmamk_f32 v97, v97, 0x3e0293ee, v102
	v_fmamk_f32 v66, v66, 0x3e0293ee, v102
	v_fmamk_f32 v67, v67, 0x3e0293ee, v102
	v_fmamk_f32 v68, v68, 0x3e0293ee, v102
	v_fmamk_f32 v69, v69, 0x3e0293ee, v102
	v_fmamk_f32 v70, v70, 0x3e0293ee, v102
	v_fmamk_f32 v71, v71, 0x3e0293ee, v102
	v_fmamk_f32 v72, v72, 0x3e0293ee, v102
	v_fmamk_f32 v73, v73, 0x3e0293ee, v102
	v_fmamk_f32 v74, v74, 0x3e0293ee, v102
	v_fmamk_f32 v75, v75, 0x3e0293ee, v102
	v_fmamk_f32 v76, v76, 0x3e0293ee, v102
	v_fmamk_f32 v77, v77, 0x3e0293ee, v102
	v_fmamk_f32 v78, v78, 0x3e0293ee, v102
	v_fmamk_f32 v79, v79, 0x3e0293ee, v102
	v_fmamk_f32 v80, v80, 0x3e0293ee, v102
	v_fmac_f32_e32 v102, 0x3e0293ee, v81
	v_exp_f32_e32 v81, v82
	v_exp_f32_e32 v82, v83
	v_exp_f32_e32 v83, v84
	v_exp_f32_e32 v84, v85
	v_exp_f32_e32 v85, v86
	v_exp_f32_e32 v86, v87
	v_exp_f32_e32 v87, v88
	v_exp_f32_e32 v88, v89
	v_exp_f32_e32 v89, v90
	v_exp_f32_e32 v90, v91
	v_exp_f32_e32 v91, v92
	v_exp_f32_e32 v92, v93
	v_exp_f32_e32 v93, v94
	v_exp_f32_e32 v94, v95
	v_exp_f32_e32 v95, v96
	v_exp_f32_e32 v96, v97
	v_exp_f32_e32 v97, v66
	v_add_f32_e32 v66, 0, v81
	v_add_f32_e32 v66, v82, v66
	v_add_f32_e32 v66, v83, v66
	v_add_f32_e32 v66, v84, v66
	v_add_f32_e32 v66, v85, v66
	v_add_f32_e32 v66, v86, v66
	v_add_f32_e32 v66, v87, v66
	v_add_f32_e32 v66, v88, v66
	v_add_f32_e32 v66, v89, v66
	v_add_f32_e32 v66, v90, v66
	v_add_f32_e32 v66, v91, v66
	v_add_f32_e32 v66, v92, v66
	v_add_f32_e32 v66, v93, v66
	v_exp_f32_e32 v103, v67
	v_add_f32_e32 v66, v94, v66
	v_exp_f32_e32 v104, v68
	v_add_f32_e32 v66, v95, v66
	v_exp_f32_e32 v105, v69
	v_add_f32_e32 v66, v96, v66
	v_exp_f32_e32 v106, v70
	v_add_f32_e32 v66, v97, v66
	v_exp_f32_e32 v107, v71
	v_add_f32_e32 v66, v103, v66
	v_exp_f32_e32 v108, v72
	v_add_f32_e32 v66, v104, v66
	v_exp_f32_e32 v109, v73
	v_add_f32_e32 v66, v105, v66
	v_exp_f32_e32 v110, v74
	v_add_f32_e32 v66, v106, v66
	v_exp_f32_e32 v111, v75
	v_add_f32_e32 v66, v107, v66
	v_exp_f32_e32 v112, v76
	v_add_f32_e32 v66, v108, v66
	v_exp_f32_e32 v113, v77
	v_add_f32_e32 v66, v109, v66
	v_exp_f32_e32 v114, v78
	v_add_f32_e32 v66, v110, v66
	v_exp_f32_e32 v115, v79
	v_add_f32_e32 v66, v111, v66
	v_exp_f32_e32 v116, v80
	v_add_f32_e32 v66, v112, v66
	v_exp_f32_e32 v102, v102
	v_add_f32_e32 v66, v113, v66
	v_add_f32_e32 v66, v114, v66
	v_add_f32_e32 v66, v115, v66
	v_add_f32_e32 v66, v116, v66
	v_add_f32_e32 v66, v102, v66
	v_mov_b32_e32 v67, v66
	s_nop 1
	v_permlane32_swap_b32_e32 v66, v67
	v_cvt_pk_bf16_f32 v68, v81, v82
	v_cvt_pk_bf16_f32 v69, v83, v84
	v_cvt_pk_bf16_f32 v70, v85, v86
	v_cvt_pk_bf16_f32 v71, v87, v88
	v_cvt_pk_bf16_f32 v72, v89, v90
	v_cvt_pk_bf16_f32 v73, v91, v92
	v_cvt_pk_bf16_f32 v74, v93, v94
	v_cvt_pk_bf16_f32 v75, v95, v96
	v_cvt_pk_bf16_f32 v76, v97, v103
	v_cvt_pk_bf16_f32 v77, v104, v105
	v_cvt_pk_bf16_f32 v78, v106, v107
	v_cvt_pk_bf16_f32 v79, v108, v109
	v_cvt_pk_bf16_f32 v80, v110, v111
	v_cvt_pk_bf16_f32 v81, v112, v113
	v_cvt_pk_bf16_f32 v82, v114, v115
	v_cvt_pk_bf16_f32 v83, v116, v102
	s_nop 0
	v_permlane32_swap_b32_e32 v68, v70
	v_permlane32_swap_b32_e32 v69, v71
	v_permlane32_swap_b32_e32 v72, v74
	v_permlane32_swap_b32_e32 v73, v75
	v_permlane32_swap_b32_e32 v76, v78
	v_permlane32_swap_b32_e32 v77, v79
	v_permlane32_swap_b32_e32 v80, v82
	v_permlane32_swap_b32_e32 v81, v83
	s_add_i32 s0, 0, 0x4000
	v_add_u32_e32 v96, s0, v171
	ds_read_b64_tr_b16 v[84:85], v96 offset:0
	ds_read_b64_tr_b16 v[86:87], v96 offset:0x800
	ds_read_b64_tr_b16 v[88:89], v96 offset:0x1000
	ds_read_b64_tr_b16 v[90:91], v96 offset:0x1800
	ds_read_b64_tr_b16 v[92:93], v96 offset:0x2000
	ds_read_b64_tr_b16 v[94:95], v96 offset:0x2800
	ds_read_b64_tr_b16 v[102:103], v96 offset:0x3000
	ds_read_b64_tr_b16 v[104:105], v96 offset:0x3800
	s_nop 0
	s_waitcnt lgkmcnt(6)
	v_mfma_f32_32x32x16_bf16 v[50:65], v[68:71], v[84:87], v[50:65]
	ds_read_b64_tr_b16 v[84:85], v96 offset:0x200
	ds_read_b64_tr_b16 v[86:87], v96 offset:0xa00
	s_waitcnt lgkmcnt(6)
	v_mfma_f32_32x32x16_bf16 v[50:65], v[72:75], v[88:91], v[50:65]
	ds_read_b64_tr_b16 v[88:89], v96 offset:0x1200
	ds_read_b64_tr_b16 v[90:91], v96 offset:0x1a00
	s_waitcnt lgkmcnt(6)
	v_mfma_f32_32x32x16_bf16 v[50:65], v[76:79], v[92:95], v[50:65]
	ds_read_b64_tr_b16 v[92:93], v96 offset:0x2200
	ds_read_b64_tr_b16 v[94:95], v96 offset:0x2a00
	s_waitcnt lgkmcnt(6)
	v_mfma_f32_32x32x16_bf16 v[50:65], v[80:83], v[102:105], v[50:65]
	ds_read_b64_tr_b16 v[102:103], v96 offset:0x3200
	ds_read_b64_tr_b16 v[104:105], v96 offset:0x3a00
	s_waitcnt lgkmcnt(6)
	v_mfma_f32_32x32x16_bf16 v[34:49], v[68:71], v[84:87], v[34:49]
	ds_read_b64_tr_b16 v[84:85], v96 offset:0x400
	ds_read_b64_tr_b16 v[86:87], v96 offset:0xc00
	s_waitcnt lgkmcnt(6)
	v_mfma_f32_32x32x16_bf16 v[34:49], v[72:75], v[88:91], v[34:49]
	ds_read_b64_tr_b16 v[88:89], v96 offset:0x1400
	ds_read_b64_tr_b16 v[90:91], v96 offset:0x1c00
	s_waitcnt lgkmcnt(6)
	v_mfma_f32_32x32x16_bf16 v[34:49], v[76:79], v[92:95], v[34:49]
	ds_read_b64_tr_b16 v[92:93], v96 offset:0x2400
	ds_read_b64_tr_b16 v[94:95], v96 offset:0x2c00
	s_waitcnt lgkmcnt(6)
	v_mfma_f32_32x32x16_bf16 v[34:49], v[80:83], v[102:105], v[34:49]
	ds_read_b64_tr_b16 v[102:103], v96 offset:0x3400
	ds_read_b64_tr_b16 v[104:105], v96 offset:0x3c00
	s_waitcnt lgkmcnt(6)
	v_mfma_f32_32x32x16_bf16 v[18:33], v[68:71], v[84:87], v[18:33]
	ds_read_b64_tr_b16 v[84:85], v96 offset:0x600
	ds_read_b64_tr_b16 v[86:87], v96 offset:0xe00
	s_waitcnt lgkmcnt(6)
	v_mfma_f32_32x32x16_bf16 v[18:33], v[72:75], v[88:91], v[18:33]
	ds_read_b64_tr_b16 v[88:89], v96 offset:0x1600
	ds_read_b64_tr_b16 v[90:91], v96 offset:0x1e00
	s_waitcnt lgkmcnt(6)
	v_mfma_f32_32x32x16_bf16 v[18:33], v[76:79], v[92:95], v[18:33]
	ds_read_b64_tr_b16 v[92:93], v96 offset:0x2600
	ds_read_b64_tr_b16 v[94:95], v96 offset:0x2e00
	s_waitcnt lgkmcnt(6)
	v_mfma_f32_32x32x16_bf16 v[18:33], v[80:83], v[102:105], v[18:33]
	ds_read_b64_tr_b16 v[102:103], v96 offset:0x3600
	ds_read_b64_tr_b16 v[104:105], v96 offset:0x3e00
	s_waitcnt lgkmcnt(6)
	v_mfma_f32_32x32x16_bf16 v[2:17], v[68:71], v[84:87], v[2:17]
	s_waitcnt lgkmcnt(0)
	s_barrier
	v_cmp_gt_u32_e32 vcc, 32, v165
	s_waitcnt lgkmcnt(4)
	v_mfma_f32_32x32x16_bf16 v[2:17], v[72:75], v[88:91], v[2:17]
	s_waitcnt lgkmcnt(2)
	v_mfma_f32_32x32x16_bf16 v[2:17], v[76:79], v[92:95], v[2:17]
	s_waitcnt lgkmcnt(0)
	v_mfma_f32_32x32x16_bf16 v[2:17], v[80:83], v[102:105], v[2:17]
	s_and_saveexec_b64 s[0:1], vcc
	s_cbranch_execz .LBB0_528
	v_fmac_f32_e32 v169, 0xbe0293ee, v101
	v_min_f32_e32 v69, 0x42f00000, v169
	v_exp_f32_e32 v69, v69
	v_add_f32_e32 v68, v98, v99
	v_fmac_f32_e32 v68, v178, v197
	v_add_f32_e32 v66, v66, v67
	v_fmac_f32_e32 v66, v68, v100
	v_add_f32_e32 v67, v69, v66
	v_cndmask_b32_e64 v66, v66, v67, s[36:37]
	ds_write_b32 v177, v66
	s_branch .LBB0_528
